# v27 plus G1 conv prologue: rows 1,2 and the 13 following rows loaded together with row 0 (one round trip instead of four serialized)
# speedup vs baseline: 1.0050x; 1.0048x over previous
; DI void g1_team(const Params& p, int j, int unit, lptr lds) {
;     ...
;         const int rb = lt / 48, cg = lt % 48, part = cg >> 4, sub = cg & 15;
;         const int col = part * 512 + h * 128 + sub * 8, t0 = 64 * n + rb * 16;
;         f32x4 wl[4][2];
; #pragma unroll
;         for (int i = 0; i < 4; ++i) { wl[i][0] = *(const f32x4*)(cw + i * 1536 + col); wl[i][1] = *(const f32x4*)(cw + i * 1536 + col + 4); }
;         u32x4 xr[19];
; #pragma unroll
;         for (int q = 0; q < 19; ++q) { const int tt = t0 - 3 + q; const int tc = tt < 0 ? 0 : tt;
;             u32x4 v = *(const u32x4*)(P + ((size_t)b * SEQ + tc) * PE + col);
;             if (tt < 0) v = (u32x4){0u, 0u, 0u, 0u};
;             xr[q] = v; }
.LBB0_365:
	s_or_b64 exec, exec, s[42:43]
	s_bfe_u32 s42, s39, 0x20006
	s_cmp_eq_u32 s42, 3
	s_cbranch_scc1 .LBB0_399
	s_movk_i32 s10, 0xab
	v_mul_lo_u16_sdwa v0, v136, s10 dst_sel:DWORD dst_unused:UNUSED_PAD src0_sel:BYTE_0 src1_sel:DWORD
	v_lshrrev_b16_e32 v137, 13, v0
	v_mul_lo_u16_e32 v0, 48, v137
	v_sub_u16_e32 v98, v136, v0
	v_bfe_u32 v109, v98, 4, 4
	v_and_b32_e32 v113, 15, v98
	v_lshlrev_b32_e32 v0, 9, v109
	s_lshl_b32 s3, s3, 7
	v_lshlrev_b32_e32 v2, 3, v113
	v_or3_b32 v35, v0, s3, v2
	v_lshlrev_b32_e32 v0, 2, v35
	s_lshl_b32 s10, s2, 6
	v_lshl_add_u64 v[14:15], s[0:1], 0, v[0:1]
	s_mov_b64 s[2:3], 0x1800
	v_lshl_add_u64 v[6:7], v[14:15], 0, s[2:3]
	s_movk_i32 s2, 0x1000
	v_add_co_u32_e32 v8, vcc, s2, v14
	s_mov_b64 s[2:3], 0x3000
	s_nop 0
	v_addc_co_u32_e32 v9, vcc, 0, v15, vcc
	v_lshl_add_u64 v[10:11], v[14:15], 0, s[2:3]
	s_movk_i32 s2, 0x3000
	v_add_co_u32_e32 v12, vcc, s2, v14
	s_mov_b64 s[2:3], 0x4800
	v_lshl_add_u32 v34, v137, 4, s10
	global_load_dwordx4 v[18:21], v0, s[0:1]
	global_load_dwordx4 v[2:5], v0, s[0:1] offset:16
	v_addc_co_u32_e32 v13, vcc, 0, v15, vcc
	v_lshl_add_u64 v[16:17], v[14:15], 0, s[2:3]
	s_movk_i32 s2, 0x4000
	v_add_u32_e32 v42, -3, v34
	s_ashr_i32 s41, s40, 31
	v_lshlrev_b32_e32 v0, 1, v35
	v_add_co_u32_e32 v14, vcc, s2, v14
	s_lshl_b64 s[2:3], s[40:41], 12
	v_lshl_add_u64 v[36:37], s[4:5], 0, v[0:1]
	v_max_i32_e32 v0, 0, v42
	v_lshl_add_u64 v[38:39], s[2:3], 0, v[0:1]
	v_mad_u64_u32 v[40:41], s[10:11], v38, s95, v[36:37]
	v_addc_co_u32_e32 v15, vcc, 0, v15, vcc
	v_mad_i32_i24 v41, v39, s95, v41
	global_load_dwordx4 v[22:25], v[8:9], off offset:2048
	s_nop 0
	global_load_dwordx4 v[6:9], v[6:7], off offset:16
	s_nop 0
	global_load_dwordx4 v[26:29], v[12:13], off
	s_nop 0
	global_load_dwordx4 v[10:13], v[10:11], off offset:16
	s_nop 0
	global_load_dwordx4 v[30:33], v[14:15], off offset:2048
	s_nop 0
	global_load_dwordx4 v[14:17], v[16:17], off offset:16
	v_max_i32_e32 v0, -1, v42
	global_load_dwordx4 v[38:41], v[40:41], off
	v_mov_b32_e32 v159, 0
	v_add_u32_e32 v158, 1, v0
	v_lshl_add_u64 v[160:161], s[2:3], 0, v[158:159]
	v_mad_u64_u32 v[162:163], s[10:11], v160, s95, v[36:37]
	v_mad_i32_i24 v163, v161, s95, v163
	global_load_dwordx4 v[164:167], v[162:163], off
	v_add_u32_e32 v158, -1, v34
	v_max_i32_e32 v158, 0, v158
	v_lshl_add_u64 v[160:161], s[2:3], 0, v[158:159]
	v_mad_u64_u32 v[162:163], s[10:11], v160, s95, v[36:37]
	v_mad_i32_i24 v163, v161, s95, v163
	global_load_dwordx4 v[168:171], v[162:163], off
	v_mov_b32_e32 v158, v34
	v_lshl_add_u64 v[160:161], s[2:3], 0, v[158:159]
	v_mad_u64_u32 v[162:163], s[10:11], v160, s95, v[36:37]
	v_mad_i32_i24 v163, v161, s95, v163
	v_mov_b32_e32 v172, s95
	v_mov_b32_e32 v173, 0
	global_load_dwordx4 v[94:97], v[162:163], off
	v_lshl_add_u64 v[162:163], v[162:163], 0, v[172:173]
	global_load_dwordx4 v[90:93], v[162:163], off
	v_lshl_add_u64 v[162:163], v[162:163], 0, v[172:173]
	global_load_dwordx4 v[86:89], v[162:163], off
	v_lshl_add_u64 v[162:163], v[162:163], 0, v[172:173]
	global_load_dwordx4 v[82:85], v[162:163], off
	v_lshl_add_u64 v[162:163], v[162:163], 0, v[172:173]
	global_load_dwordx4 v[78:81], v[162:163], off
	v_lshl_add_u64 v[162:163], v[162:163], 0, v[172:173]
	global_load_dwordx4 v[74:77], v[162:163], off
	v_lshl_add_u64 v[162:163], v[162:163], 0, v[172:173]
	global_load_dwordx4 v[70:73], v[162:163], off
	v_lshl_add_u64 v[162:163], v[162:163], 0, v[172:173]
	global_load_dwordx4 v[66:69], v[162:163], off
	v_lshl_add_u64 v[162:163], v[162:163], 0, v[172:173]
	global_load_dwordx4 v[62:65], v[162:163], off
	v_lshl_add_u64 v[162:163], v[162:163], 0, v[172:173]
	global_load_dwordx4 v[58:61], v[162:163], off
	v_lshl_add_u64 v[162:163], v[162:163], 0, v[172:173]
	global_load_dwordx4 v[54:57], v[162:163], off
	v_lshl_add_u64 v[162:163], v[162:163], 0, v[172:173]
	global_load_dwordx4 v[50:53], v[162:163], off
	v_lshl_add_u64 v[162:163], v[162:163], 0, v[172:173]
	global_load_dwordx4 v[46:49], v[162:163], off
	v_cmp_eq_u32_e32 vcc, 0, v34
	v_add_u32_e32 v0, 1, v0
	v_mov_b32_e32 v35, v1
	v_cmp_lt_u16_sdwa s[40:41], v98, v206 src0_sel:BYTE_0 src1_sel:DWORD
	s_waitcnt vmcnt(22)
	v_mov_b32_e32 v114, v4
	s_waitcnt vmcnt(20)
	v_mov_b32_e32 v115, v8
	s_waitcnt vmcnt(18)
	v_mov_b32_e32 v119, v12
	s_waitcnt vmcnt(16)
	v_mov_b32_e32 v118, v16
	v_mov_b32_e32 v127, v13
	s_waitcnt vmcnt(15)
	v_cndmask_b32_e64 v130, v39, 0, vcc
	v_cndmask_b32_e64 v131, v38, 0, vcc
	v_lshl_add_u64 v[38:39], s[2:3], 0, v[0:1]
	v_cndmask_b32_e64 v132, v40, 0, vcc
	v_cndmask_b32_e64 v100, v41, 0, vcc
	v_mad_u64_u32 v[40:41], s[10:11], v38, s95, v[36:37]
	v_mad_i32_i24 v41, v39, s95, v41
	v_add_u32_e32 v0, -1, v34
	v_max_i32_e32 v0, 0, v0
	v_lshlrev_b32_e32 v98, 16, v100
	v_and_b32_e32 v100, 0xffff0000, v100
	s_waitcnt vmcnt(14)
	v_cndmask_b32_e64 v102, v165, 0, vcc
	v_cndmask_b32_e64 v103, v164, 0, vcc
	v_lshl_add_u64 v[38:39], s[2:3], 0, v[0:1]
	v_cndmask_b32_e64 v101, v167, 0, vcc
	v_cndmask_b32_e64 v99, v166, 0, vcc
	v_mad_u64_u32 v[40:41], s[10:11], v38, s95, v[36:37]
	v_mad_i32_i24 v41, v39, s95, v41
	v_or_b32_e32 v0, 1, v34
	v_lshlrev_b32_e32 v108, 16, v101
	v_lshlrev_b32_e32 v110, 16, v99
	v_and_b32_e32 v111, 0xffff0000, v99
	v_mov_b32_e32 v99, v108
	v_pk_mul_f32 v[98:99], v[114:115], v[98:99]
	v_lshlrev_b32_e32 v128, 16, v103
	v_and_b32_e32 v129, 0xffff0000, v103
	v_lshlrev_b32_e32 v116, 16, v102
	v_and_b32_e32 v117, 0xffff0000, v102
	v_and_b32_e32 v112, 0xffff0000, v101
	v_mov_b32_e32 v101, v112
	s_waitcnt vmcnt(13)
; DI float bflo(unsigned w) { return __uint_as_float(w << 16); }
; DI float bfhi(unsigned w) { return __uint_as_float(w & 0xffff0000u); }
; DI float sigmoidf_(float x) { return 1.f / (1.f + __expf(-x)); }
; DI void g1_team(const Params& p, int j, int unit, lptr lds) {
;     ...
;         for (int q = 0; q < 19; ++q) { const int tt = t0 - 3 + q; const int tc = tt < 0 ? 0 : tt;
;             u32x4 v = *(const u32x4*)(P + ((size_t)b * SEQ + tc) * PE + col);
;             if (tt < 0) v = (u32x4){0u, 0u, 0u, 0u};
;             xr[q] = v; }
; #pragma unroll
;         for (int i = 0; i < 16; ++i) {
;             float acc[8]; for (int e = 0; e < 8; ++e) acc[e] = 0.f;
; #pragma unroll
;             for (int tp = 0; tp < 4; ++tp) { const u32x4 x = xr[i + tp]; const f32x4 w0 = wl[tp][0], w1 = wl[tp][1];
;                 acc[0] += w0[0] * bflo(x.x); acc[1] += w0[1] * bfhi(x.x); acc[2] += w0[2] * bflo(x.y); acc[3] += w0[3] * bfhi(x.y);
;                 acc[4] += w1[0] * bflo(x.z); acc[5] += w1[1] * bfhi(x.z); acc[6] += w1[2] * bflo(x.w); acc[7] += w1[3] * bfhi(x.w); }
;             float ss = 0.f;
;             for (int e = 0; e < 8; ++e) { acc[e] = acc[e] * sigmoidf_(acc[e]); ss += acc[e] * acc[e]; }
	v_cndmask_b32_e64 v105, v169, 0, vcc
	v_cndmask_b32_e64 v106, v168, 0, vcc
	v_lshl_add_u64 v[38:39], s[2:3], 0, v[34:35]
	v_cndmask_b32_e64 v104, v170, 0, vcc
	v_cndmask_b32_e64 v126, v171, 0, vcc
	v_mad_u64_u32 v[40:41], s[10:11], v38, s95, v[36:37]
	v_mad_i32_i24 v41, v39, s95, v41
	v_lshl_add_u64 v[38:39], s[2:3], 0, v[0:1]
	v_mad_u64_u32 v[40:41], s[10:11], v38, s95, v[36:37]
	v_or_b32_e32 v0, 2, v34
	v_mad_i32_i24 v41, v39, s95, v41
	v_lshl_add_u64 v[38:39], s[2:3], 0, v[0:1]
	v_mad_u64_u32 v[40:41], s[10:11], v38, s95, v[36:37]
	v_or_b32_e32 v0, 3, v34
	v_mad_i32_i24 v41, v39, s95, v41
	v_lshl_add_u64 v[38:39], s[2:3], 0, v[0:1]
	v_mad_u64_u32 v[40:41], s[10:11], v38, s95, v[36:37]
	v_or_b32_e32 v0, 4, v34
	v_mad_i32_i24 v41, v39, s95, v41
	v_lshl_add_u64 v[38:39], s[2:3], 0, v[0:1]
	v_mad_u64_u32 v[40:41], s[10:11], v38, s95, v[36:37]
	v_or_b32_e32 v0, 5, v34
	v_mad_i32_i24 v41, v39, s95, v41
	v_lshl_add_u64 v[38:39], s[2:3], 0, v[0:1]
	v_mad_u64_u32 v[40:41], s[10:11], v38, s95, v[36:37]
	v_or_b32_e32 v0, 6, v34
	v_mad_i32_i24 v41, v39, s95, v41
	v_lshl_add_u64 v[38:39], s[2:3], 0, v[0:1]
	v_mad_u64_u32 v[40:41], s[10:11], v38, s95, v[36:37]
	v_or_b32_e32 v0, 7, v34
	v_mad_i32_i24 v41, v39, s95, v41
	v_lshl_add_u64 v[38:39], s[2:3], 0, v[0:1]
	v_mad_u64_u32 v[40:41], s[10:11], v38, s95, v[36:37]
	v_or_b32_e32 v0, 8, v34
	v_mad_i32_i24 v41, v39, s95, v41
	v_lshl_add_u64 v[38:39], s[2:3], 0, v[0:1]
	v_mad_u64_u32 v[40:41], s[10:11], v38, s95, v[36:37]
	v_or_b32_e32 v0, 9, v34
	v_mad_i32_i24 v41, v39, s95, v41
	v_lshl_add_u64 v[38:39], s[2:3], 0, v[0:1]
	v_mad_u64_u32 v[40:41], s[10:11], v38, s95, v[36:37]
	v_or_b32_e32 v0, 10, v34
	v_mad_i32_i24 v41, v39, s95, v41
	v_lshl_add_u64 v[38:39], s[2:3], 0, v[0:1]
	v_mad_u64_u32 v[40:41], s[10:11], v38, s95, v[36:37]
	v_or_b32_e32 v0, 11, v34
	v_mad_i32_i24 v41, v39, s95, v41
	v_lshl_add_u64 v[38:39], s[2:3], 0, v[0:1]
	v_mad_u64_u32 v[40:41], s[10:11], v38, s95, v[36:37]
	v_or_b32_e32 v0, 12, v34
	v_mad_i32_i24 v41, v39, s95, v41
	v_lshl_add_u64 v[38:39], s[2:3], 0, v[0:1]
	v_mad_u64_u32 v[40:41], s[10:11], v38, s95, v[36:37]
	v_or_b32_e32 v0, 13, v34
	v_mad_i32_i24 v41, v39, s95, v41
	v_lshl_add_u64 v[38:39], s[2:3], 0, v[0:1]
	v_mad_u64_u32 v[40:41], s[10:11], v38, s95, v[36:37]
	v_or_b32_e32 v0, 14, v34
	v_mad_i32_i24 v41, v39, s95, v41
	v_lshl_add_u64 v[38:39], s[2:3], 0, v[0:1]
	v_or_b32_e32 v0, 15, v34
	v_lshl_add_u64 v[34:35], s[2:3], 0, v[0:1]
	v_add_f32_e32 v0, 0, v98
	s_waitcnt vmcnt(12)
	v_lshlrev_b32_e32 v102, 16, v97
	v_lshlrev_b32_e32 v103, 16, v126
	v_add_f32_e32 v0, v0, v99
	v_mov_b32_e32 v98, v5
	v_mov_b32_e32 v99, v9
	v_lshlrev_b32_e32 v124, 16, v106
	v_and_b32_e32 v125, 0xffff0000, v106
	v_pk_mul_f32 v[106:107], v[118:119], v[102:103]
	v_pk_mul_f32 v[100:101], v[98:99], v[100:101]
	v_add_f32_e32 v0, v0, v107
	v_add_f32_e32 v100, 0, v100
	v_add_f32_e32 v144, v106, v0
	v_and_b32_e32 v107, 0xffff0000, v126
	v_and_b32_e32 v106, 0xffff0000, v97
	v_mov_b32_e32 v126, v17
	v_add_f32_e32 v133, v100, v101
	v_lshlrev_b32_e32 v122, 16, v105
	v_and_b32_e32 v123, 0xffff0000, v105
	v_lshlrev_b32_e32 v120, 16, v104
	v_and_b32_e32 v121, 0xffff0000, v104
	v_lshlrev_b32_e32 v104, 16, v94
	v_and_b32_e32 v105, 0xffff0000, v94
	v_lshlrev_b32_e32 v100, 16, v95
	v_and_b32_e32 v101, 0xffff0000, v95
	v_lshlrev_b32_e32 v94, 16, v96
	v_and_b32_e32 v95, 0xffff0000, v96
	v_pk_mul_f32 v[96:97], v[126:127], v[106:107]
	global_load_dwordx4 v[42:45], v[40:41], off
	v_add_f32_e32 v0, v133, v97
	v_add_f32_e32 v0, v96, v0
	v_lshlrev_b32_e32 v96, 16, v131
	v_and_b32_e32 v97, 0xffff0000, v131
	v_pk_fma_f32 v[96:97], v[18:19], v[96:97], 0 op_sel_hi:[1,1,0]
	v_mad_u64_u32 v[40:41], s[10:11], v38, s95, v[36:37]
	v_pk_fma_f32 v[96:97], v[22:23], v[128:129], v[96:97]
	v_mad_u64_u32 v[36:37], s[2:3], v34, s95, v[36:37]
	v_pk_fma_f32 v[96:97], v[26:27], v[124:125], v[96:97]
	v_mad_i32_i24 v41, v39, s95, v41
	v_pk_fma_f32 v[96:97], v[30:31], v[104:105], v[96:97]
	v_mad_i32_i24 v37, v35, s95, v37
	v_mul_f32_e32 v131, 0xbfb8aa3b, v96
	v_exp_f32_e32 v138, v131
	v_mul_f32_e32 v131, 0xbfb8aa3b, v97
	v_exp_f32_e32 v139, v131
	global_load_dwordx4 v[38:41], v[40:41], off
	v_pk_add_f32 v[138:139], v[138:139], 1.0 op_sel_hi:[1,0]
	s_nop 0
	v_div_scale_f32 v131, s[2:3], v139, v139, 1.0
	v_rcp_f32_e32 v133, v131
	global_load_dwordx4 v[34:37], v[36:37], off
	v_fma_f32 v140, -v131, v133, 1.0
	v_fmac_f32_e32 v133, v140, v133
	v_div_scale_f32 v140, vcc, 1.0, v139, 1.0
	v_mul_f32_e32 v141, v140, v133
	v_fma_f32 v142, -v131, v141, v140
	v_fmac_f32_e32 v141, v142, v133
	v_fma_f32 v131, -v131, v141, v140
	v_div_fmas_f32 v131, v131, v133, v141
	v_div_fixup_f32 v139, v131, v139, 1.0
	v_div_scale_f32 v131, s[2:3], v138, v138, 1.0
	v_rcp_f32_e32 v133, v131
	s_nop 0
	v_fma_f32 v140, -v131, v133, 1.0
	v_fmac_f32_e32 v133, v140, v133
	v_div_scale_f32 v140, vcc, 1.0, v138, 1.0
	v_mul_f32_e32 v141, v140, v133
	v_fma_f32 v142, -v131, v141, v140
	v_fmac_f32_e32 v141, v142, v133
	v_fma_f32 v131, -v131, v141, v140
	v_div_fmas_f32 v131, v131, v133, v141
	v_lshlrev_b32_e32 v140, 16, v130
	v_and_b32_e32 v141, 0xffff0000, v130
	v_div_fixup_f32 v138, v131, v138, 1.0
	v_pk_fma_f32 v[130:131], v[20:21], v[140:141], 0 op_sel_hi:[1,1,0]
	v_pk_mul_f32 v[96:97], v[96:97], v[138:139]
	v_pk_fma_f32 v[130:131], v[24:25], v[116:117], v[130:131]
; DI float shx(float v, int m) { const int lane = tid_() & 63; return __builtin_bit_cast(float, __builtin_amdgcn_ds_bpermute((lane ^ m) << 2, __builtin_bit_cast(int, v))); }
; DI float sigmoidf_(float x) { return 1.f / (1.f + __expf(-x)); }
; DI void g1_team(const Params& p, int j, int unit, lptr lds) {
;     ...
;             float ss = 0.f;
;             for (int e = 0; e < 8; ++e) { acc[e] = acc[e] * sigmoidf_(acc[e]); ss += acc[e] * acc[e]; }
;             ss += shx(ss, 1); ss += shx(ss, 2); ss += shx(ss, 4); ss += shx(ss, 8);
;             if (part < 2) { const float rn = rsqrtf(ss + EPS); for (int e = 0; e < 8; ++e) acc[e] *= rn; }
	v_pk_mul_f32 v[138:139], v[96:97], v[96:97]
	v_pk_fma_f32 v[130:131], v[28:29], v[122:123], v[130:131]
	v_add_f32_e32 v138, v138, v139
	v_pk_fma_f32 v[130:131], v[32:33], v[100:101], v[130:131]
	s_nop 0
	v_mul_f32_e32 v133, 0xbfb8aa3b, v130
	v_exp_f32_e32 v140, v133
	v_mul_f32_e32 v133, 0xbfb8aa3b, v131
	v_exp_f32_e32 v141, v133
	s_nop 0
	v_pk_add_f32 v[140:141], v[140:141], 1.0 op_sel_hi:[1,0]
	s_nop 0
	v_div_scale_f32 v133, s[2:3], v141, v141, 1.0
	v_rcp_f32_e32 v142, v133
	s_nop 0
	v_fma_f32 v143, -v133, v142, 1.0
	v_fmac_f32_e32 v142, v143, v142
	v_div_scale_f32 v143, vcc, 1.0, v141, 1.0
	v_mul_f32_e32 v145, v143, v142
	v_fma_f32 v146, -v133, v145, v143
	v_fmac_f32_e32 v145, v146, v142
	v_fma_f32 v133, -v133, v145, v143
	v_div_fmas_f32 v133, v133, v142, v145
	v_div_fixup_f32 v141, v133, v141, 1.0
	v_div_scale_f32 v133, s[2:3], v140, v140, 1.0
	v_rcp_f32_e32 v142, v133
	s_nop 0
	v_fma_f32 v143, -v133, v142, 1.0
	v_fmac_f32_e32 v142, v143, v142
	v_div_scale_f32 v143, vcc, 1.0, v140, 1.0
	v_mul_f32_e32 v145, v143, v142
	v_fma_f32 v146, -v133, v145, v143
	v_fmac_f32_e32 v145, v146, v142
	v_fma_f32 v133, -v133, v145, v143
	v_div_fmas_f32 v133, v133, v142, v145
	v_lshlrev_b32_e32 v142, 16, v132
	v_and_b32_e32 v143, 0xffff0000, v132
	v_div_fixup_f32 v140, v133, v140, 1.0
	v_pk_fma_f32 v[132:133], v[2:3], v[142:143], 0 op_sel_hi:[1,1,0]
	v_pk_mul_f32 v[130:131], v[130:131], v[140:141]
	v_pk_fma_f32 v[132:133], v[6:7], v[110:111], v[132:133]
	v_pk_mul_f32 v[140:141], v[130:131], v[130:131]
	v_pk_fma_f32 v[132:133], v[10:11], v[120:121], v[132:133]
	v_add_f32_e32 v138, v140, v138
	v_pk_fma_f32 v[132:133], v[14:15], v[94:95], v[132:133]
	v_add_f32_e32 v138, v141, v138
	v_mul_f32_e32 v142, 0xbfb8aa3b, v132
	v_mul_f32_e32 v143, 0xbfb8aa3b, v133
	v_exp_f32_e32 v142, v142
	v_exp_f32_e32 v143, v143
	s_nop 0
	v_pk_add_f32 v[142:143], v[142:143], 1.0 op_sel_hi:[1,0]
	s_nop 0
	v_div_scale_f32 v145, s[2:3], v143, v143, 1.0
	v_rcp_f32_e32 v146, v145
	s_nop 0
	v_fma_f32 v147, -v145, v146, 1.0
	v_fmac_f32_e32 v146, v147, v146
	v_div_scale_f32 v147, vcc, 1.0, v143, 1.0
	v_mul_f32_e32 v153, v147, v146
	v_fma_f32 v154, -v145, v153, v147
	v_fmac_f32_e32 v153, v154, v146
	v_fma_f32 v145, -v145, v153, v147
	v_div_fmas_f32 v145, v145, v146, v153
	v_div_fixup_f32 v143, v145, v143, 1.0
	v_div_scale_f32 v145, s[2:3], v142, v142, 1.0
	v_rcp_f32_e32 v146, v145
	s_nop 0
	v_fma_f32 v147, -v145, v146, 1.0
	v_fmac_f32_e32 v146, v147, v146
	v_div_scale_f32 v147, vcc, 1.0, v142, 1.0
	v_mul_f32_e32 v153, v147, v146
	v_fma_f32 v154, -v145, v153, v147
	v_fmac_f32_e32 v153, v154, v146
	v_fma_f32 v145, -v145, v153, v147
	v_div_fmas_f32 v145, v145, v146, v153
	v_div_fixup_f32 v142, v145, v142, 1.0
	v_pk_mul_f32 v[132:133], v[132:133], v[142:143]
	s_nop 0
	v_pk_mul_f32 v[142:143], v[132:133], v[132:133]
	s_nop 0
	v_add_f32_e32 v138, v142, v138
	v_add_f32_e32 v140, v143, v138
	v_mul_f32_e32 v138, 0xbfb8aa3b, v144
	v_exp_f32_e32 v138, v138
	s_nop 0
	v_add_f32_e32 v138, 1.0, v138
	v_div_scale_f32 v139, s[2:3], v138, v138, 1.0
	v_rcp_f32_e32 v141, v139
	s_nop 0
	v_fma_f32 v142, -v139, v141, 1.0
	v_fmac_f32_e32 v141, v142, v141
	v_div_scale_f32 v142, vcc, 1.0, v138, 1.0
	v_mul_f32_e32 v143, v142, v141
	v_fma_f32 v145, -v139, v143, v142
	v_fmac_f32_e32 v143, v145, v141
	v_fma_f32 v139, -v139, v143, v142
	v_div_fmas_f32 v139, v139, v141, v143
	v_div_fixup_f32 v138, v139, v138, 1.0
	v_mul_f32_e32 v139, 0xbfb8aa3b, v0
	v_exp_f32_e32 v139, v139
	v_mul_f32_e32 v138, v144, v138
	v_fmac_f32_e32 v140, v138, v138
	v_add_f32_e32 v139, 1.0, v139
	v_div_scale_f32 v141, s[2:3], v139, v139, 1.0
	v_rcp_f32_e32 v142, v141
	s_nop 0
	v_fma_f32 v143, -v141, v142, 1.0
	v_fmac_f32_e32 v142, v143, v142
	v_div_scale_f32 v143, vcc, 1.0, v139, 1.0
	v_mul_f32_e32 v144, v143, v142
	v_fma_f32 v145, -v141, v144, v143
	v_fmac_f32_e32 v144, v145, v142
	v_fma_f32 v141, -v141, v144, v143
	v_div_fmas_f32 v141, v141, v142, v144
	v_div_fixup_f32 v139, v141, v139, 1.0
	v_mul_f32_e32 v139, v0, v139
	v_mov_b32_e32 v0, v194
	v_fmac_f32_e32 v140, v139, v139
	v_lshlrev_b32_e32 v0, 2, v0
	v_bitop3_b32 v0, v0, 4, v199 bitop3:0x6c
	ds_bpermute_b32 v0, v0, v140
	s_waitcnt lgkmcnt(0)
	v_add_f32_e32 v0, v140, v0
	v_mov_b32_e32 v140, v194
	s_nop 0
	v_lshlrev_b32_e32 v140, 2, v140
	v_bitop3_b32 v140, v140, 8, v199 bitop3:0x6c
	ds_bpermute_b32 v140, v140, v0
	s_waitcnt lgkmcnt(0)
	v_add_f32_e32 v0, v0, v140
	v_mov_b32_e32 v140, v194
	s_nop 0
	v_lshlrev_b32_e32 v140, 2, v140
	v_bitop3_b32 v140, v140, 16, v199 bitop3:0x6c
	ds_bpermute_b32 v140, v140, v0
	s_waitcnt lgkmcnt(0)
	v_add_f32_e32 v0, v0, v140
	v_mov_b32_e32 v140, v194
	s_nop 0
	v_lshlrev_b32_e32 v140, 2, v140
	v_bitop3_b32 v140, v140, 32, v199 bitop3:0x6c
	ds_bpermute_b32 v140, v140, v0
	s_and_saveexec_b64 s[2:3], s[40:41]
	s_cbranch_execz .LBB0_368
	s_waitcnt lgkmcnt(0)
	v_add_f32_e32 v0, v0, v140
	v_add_f32_e32 v0, 0x358637bd, v0
	v_mul_f32_e32 v140, 0x4b800000, v0
	v_cmp_gt_f32_e32 vcc, s72, v0
	s_nop 1
	v_cndmask_b32_e32 v0, v0, v140, vcc
	v_rsq_f32_e32 v0, v0
	s_nop 0
	v_mul_f32_e32 v140, 0x45800000, v0
	v_cndmask_b32_e32 v0, v0, v140, vcc
	v_pk_mul_f32 v[96:97], v[96:97], v[0:1] op_sel_hi:[1,0]
	v_pk_mul_f32 v[130:131], v[130:131], v[0:1] op_sel_hi:[1,0]
	v_pk_mul_f32 v[132:133], v[132:133], v[0:1] op_sel_hi:[1,0]
	v_mul_f32_e32 v138, v138, v0
	v_mul_f32_e32 v139, v139, v0
